# v31 + s_sleep 64 at the head of each sample-side chain in P5 (spreads the sample side's memory traffic so it interferes less with the prompt chains)
# speedup vs baseline: 1.0086x; 1.0086x over previous
.LBB0_1982:
	s_sleep 64
	v_readfirstlane_b32 s56, v37
	s_lshr_b32 s13, s56, 6
	s_lshl_b32 s12, s13, 4
	v_or_b32_e32 v52, s12, v36
	s_and_b64 vcc, exec, s[10:11]
	v_lshl_add_u64 v[2:3], s[60:61], 0, v[46:47]
	v_mov_b32_e32 v54, 0
	v_mov_b32_e32 v55, 0
	v_mov_b32_e32 v56, 0
	v_mov_b32_e32 v57, 0
	v_mov_b32_e32 v60, 0
	v_mov_b32_e32 v61, 0
	v_mov_b32_e32 v64, 0
	v_mov_b32_e32 v65, 0
	v_mov_b32_e32 v58, 0
	v_mov_b32_e32 v59, 0
	v_mov_b32_e32 v68, 0
	v_mov_b32_e32 v69, 0
	v_mov_b32_e32 v66, 0
	v_mov_b32_e32 v67, 0
	v_mov_b32_e32 v74, 0
	v_mov_b32_e32 v75, 0
	v_mov_b32_e32 v62, 0
	v_mov_b32_e32 v63, 0
	v_mov_b32_e32 v70, 0
	v_mov_b32_e32 v71, 0
	v_mov_b32_e32 v76, 0
	v_mov_b32_e32 v77, 0
	v_mov_b32_e32 v78, 0
	v_mov_b32_e32 v79, 0
	v_mov_b32_e32 v72, 0
	v_mov_b32_e32 v73, 0
	v_mov_b32_e32 v80, 0
	v_mov_b32_e32 v81, 0
	v_mov_b32_e32 v82, 0
	v_mov_b32_e32 v83, 0
	v_mov_b32_e32 v84, 0
	v_mov_b32_e32 v85, 0
	s_cbranch_vccnz .Ls0_skip
	v_mov_b32_e32 v53, v35
	v_lshlrev_b64 v[4:5], 9, v[52:53]
	v_lshl_add_u64 v[4:5], v[2:3], 0, v[4:5]
	global_load_dword v54, v[4:5], off nt
	global_load_dword v55, v[4:5], off offset:512 nt
	global_load_dword v56, v[4:5], off offset:1024 nt
	global_load_dword v57, v[4:5], off offset:1536 nt
	global_load_dword v60, v[4:5], off offset:64 nt
	global_load_dword v61, v[4:5], off offset:576 nt
	global_load_dword v64, v[4:5], off offset:1088 nt
	global_load_dword v65, v[4:5], off offset:1600 nt
	global_load_dword v58, v[4:5], off offset:128 nt
	global_load_dword v59, v[4:5], off offset:640 nt
	global_load_dword v68, v[4:5], off offset:1152 nt
	global_load_dword v69, v[4:5], off offset:1664 nt
	global_load_dword v66, v[4:5], off offset:192 nt
	global_load_dword v67, v[4:5], off offset:704 nt
	global_load_dword v74, v[4:5], off offset:1216 nt
	global_load_dword v75, v[4:5], off offset:1728 nt
	global_load_dword v62, v[4:5], off offset:256 nt
	global_load_dword v63, v[4:5], off offset:768 nt
	global_load_dword v70, v[4:5], off offset:1280 nt
	global_load_dword v71, v[4:5], off offset:1792 nt
	global_load_dword v76, v[4:5], off offset:320 nt
	global_load_dword v77, v[4:5], off offset:832 nt
	global_load_dword v78, v[4:5], off offset:1344 nt
	global_load_dword v79, v[4:5], off offset:1856 nt
	global_load_dword v72, v[4:5], off offset:384 nt
	global_load_dword v73, v[4:5], off offset:896 nt
	global_load_dword v80, v[4:5], off offset:1408 nt
	global_load_dword v81, v[4:5], off offset:1920 nt
	global_load_dword v82, v[4:5], off offset:448 nt
	global_load_dword v83, v[4:5], off offset:960 nt
	global_load_dword v84, v[4:5], off offset:1472 nt
	global_load_dword v85, v[4:5], off offset:1984 nt
